# P0 weight-transpose stores carry the nt hint too
# speedup vs baseline: 1.0107x; 1.0077x over previous
; #define LAS __attribute__((address_space(3)))
; __device__ __forceinline__ unsigned cvt_pk_bf16(float lo, float hi) { unsigned r; asm("v_cvt_pk_bf16_f32 %0, %1, %2" : "=v"(r) : "v"(lo), "v"(hi)); return r; }
; __device__ __forceinline__ float bf_lo(unsigned w) { return __uint_as_float(w << 16); }
; __device__ __forceinline__ float bf_hi(unsigned w) { return __uint_as_float(w & 0xffff0000u); }
; __device__ __forceinline__ void transpose_item(const float* W, int K, int N, bf16_t* WT, int ldt, int k0, int n0, int drow0, LAS float* scr, int lane,
;                                                const float* gam = nullptr, const float* bet = nullptr, float* csp = nullptr, float* bcp = nullptr) {
;     ...
;     for (int j = 0; j < 4; ++j) { const int n = (lane >> 3) + 8 * j; const LAS float* sp = scr + (8 * c) * 33 + n;
;         float w[8];
; #pragma unroll
;         for (int e = 0; e < 8; ++e) w[e] = sp[e * 33];
;         u32x4 o; o.x = cvt_pk_bf16(w[0] * ge[0], w[1] * ge[1]); o.y = cvt_pk_bf16(w[2] * ge[2], w[3] * ge[3]); o.z = cvt_pk_bf16(w[4] * ge[4], w[5] * ge[5]); o.w = cvt_pk_bf16(w[6] * ge[6], w[7] * ge[7]);
;         *(u32x4*)(WT + (size_t)(drow0 + n) * ldt + k0 + 8 * c) = o;
;         if (gam) {
;             float cs = (bf_lo(o.x) + bf_hi(o.x)) + (bf_lo(o.y) + bf_hi(o.y)) + (bf_lo(o.z) + bf_hi(o.z)) + (bf_lo(o.w) + bf_hi(o.w)), bc = 0.f;
; #pragma unroll
;             for (int e = 0; e < 8; ++e) bc += w[e] * be[e];
;             cs += __shfl_xor(cs, 1); cs += __shfl_xor(cs, 2); cs += __shfl_xor(cs, 4); bc += __shfl_xor(bc, 1); bc += __shfl_xor(bc, 2); bc += __shfl_xor(bc, 4);
;             if (c == 0) { csp[(size_t)(k0 >> 6) * N + n0 + n] = cs; bcp[(size_t)(k0 >> 6) * N + n0 + n] = bc; }
;         }
.LBB0_129:
	ds_read2_b32 v[46:47], v13 offset1:33
	ds_read2_b32 v[44:45], v13 offset0:66 offset1:99
	ds_read2_b32 v[42:43], v13 offset0:132 offset1:165
	ds_read2_b32 v[40:41], v13 offset0:198 offset1:231
	s_lshl_b32 s23, s23, 1
	s_add_u32 s20, s20, s23
	s_waitcnt vmcnt(0) lgkmcnt(2)
	v_mul_f32_e32 v4, v63, v45
	v_mul_f32_e32 v2, v55, v46
	v_mul_f32_e32 v3, v58, v47
	v_cvt_pk_bf16_f32 v2, v2, v3
	v_mul_f32_e32 v3, v60, v44
	v_cvt_pk_bf16_f32 v3, v3, v4
	s_waitcnt lgkmcnt(1)
	v_mul_f32_e32 v4, v65, v42
	v_mul_f32_e32 v5, v67, v43
	s_addc_u32 s21, s21, 0
	v_cvt_pk_bf16_f32 v4, v4, v5
	s_waitcnt lgkmcnt(0)
	v_mul_f32_e32 v5, v69, v40
	v_mul_f32_e32 v72, v71, v41
	v_lshl_add_u64 v[38:39], s[20:21], 0, v[6:7]
	s_lshl_b32 s20, s22, 10
	v_cvt_pk_bf16_f32 v5, v5, v72
	v_lshlrev_b32_e32 v72, 11, v62
	v_mov_b32_e32 v73, v7
	s_or_b32 s18, s20, s18
	v_lshl_add_u64 v[72:73], v[38:39], 0, v[72:73]
	s_and_b64 vcc, exec, s[4:5]
	global_store_dwordx4 v[72:73], v[2:5], off nt
	s_cbranch_vccnz .LBB0_133
	v_lshlrev_b32_e32 v62, 16, v2
	v_and_b32_e32 v2, 0xffff0000, v2
	v_lshlrev_b32_e32 v72, 16, v3
	v_and_b32_e32 v3, 0xffff0000, v3
	v_add_f32_e32 v3, v72, v3
	v_lshlrev_b32_e32 v72, 16, v4
	v_and_b32_e32 v4, 0xffff0000, v4
	v_add_f32_e32 v2, v62, v2
	v_add_f32_e32 v4, v72, v4
	v_add_f32_e32 v2, v2, v3
	v_add_f32_e32 v2, v2, v4
	v_and_b32_e32 v4, 64, v52
	v_xor_b32_e32 v3, 1, v52
	v_add_u32_e32 v4, 64, v4
	v_lshlrev_b32_e32 v72, 16, v5
	v_and_b32_e32 v5, 0xffff0000, v5
	v_cmp_lt_i32_e32 vcc, v3, v4
	v_add_f32_e32 v5, v72, v5
	v_fma_f32 v46, v54, v46, 0
	v_cndmask_b32_e32 v3, v52, v3, vcc
	v_fmac_f32_e32 v46, v56, v47
	v_add_f32_e32 v2, v2, v5
	v_lshlrev_b32_e32 v3, 2, v3
	v_fmac_f32_e32 v46, v59, v44
	ds_bpermute_b32 v5, v3, v2
	v_fmac_f32_e32 v46, v61, v45
	v_fmac_f32_e32 v46, v64, v42
	v_fmac_f32_e32 v46, v66, v43
	v_fmac_f32_e32 v46, v68, v40
	s_waitcnt lgkmcnt(0)
	v_add_f32_e32 v2, v2, v5
	v_xor_b32_e32 v5, 2, v52
	v_fmac_f32_e32 v46, v70, v41
	v_cmp_lt_i32_e32 vcc, v5, v4
	ds_bpermute_b32 v3, v3, v46
	s_waitcnt lgkmcnt(0)
	v_add_f32_e32 v41, v46, v3
	v_cndmask_b32_e32 v5, v52, v5, vcc
	v_lshlrev_b32_e32 v5, 2, v5
	ds_bpermute_b32 v40, v5, v2
	ds_bpermute_b32 v5, v5, v41
	s_waitcnt lgkmcnt(1)
	v_add_f32_e32 v2, v2, v40
	v_xor_b32_e32 v40, 4, v52
	v_cmp_lt_i32_e32 vcc, v40, v4
	s_waitcnt lgkmcnt(0)
	v_add_f32_e32 v4, v41, v5
	v_cndmask_b32_e32 v3, v52, v40, vcc
	v_lshlrev_b32_e32 v40, 2, v3
	ds_bpermute_b32 v3, v40, v2
	ds_bpermute_b32 v5, v40, v4
	s_and_saveexec_b64 s[20:21], s[0:1]
	s_cbranch_execz .LBB0_132
	v_or_b32_e32 v40, s18, v10
	v_lshlrev_b32_e32 v40, 2, v40
	s_waitcnt lgkmcnt(1)
	v_add_f32_e32 v2, v2, v3
	s_waitcnt lgkmcnt(0)
	v_add_f32_e32 v3, v4, v5
	global_store_dword v40, v2, s[8:9]
	global_store_dword v40, v3, s[10:11]

; #define LAS __attribute__((address_space(3)))
; __device__ __forceinline__ unsigned cvt_pk_bf16(float lo, float hi) { unsigned r; asm("v_cvt_pk_bf16_f32 %0, %1, %2" : "=v"(r) : "v"(lo), "v"(hi)); return r; }
; __device__ __forceinline__ float bf_lo(unsigned w) { return __uint_as_float(w << 16); }
; __device__ __forceinline__ float bf_hi(unsigned w) { return __uint_as_float(w & 0xffff0000u); }
; __device__ __forceinline__ void transpose_item(const float* W, int K, int N, bf16_t* WT, int ldt, int k0, int n0, int drow0, LAS float* scr, int lane,
;                                                const float* gam = nullptr, const float* bet = nullptr, float* csp = nullptr, float* bcp = nullptr) {
;     ...
;     for (int j = 0; j < 4; ++j) { const int n = (lane >> 3) + 8 * j; const LAS float* sp = scr + (8 * c) * 33 + n;
;         float w[8];
; #pragma unroll
;         for (int e = 0; e < 8; ++e) w[e] = sp[e * 33];
;         u32x4 o; o.x = cvt_pk_bf16(w[0] * ge[0], w[1] * ge[1]); o.y = cvt_pk_bf16(w[2] * ge[2], w[3] * ge[3]); o.z = cvt_pk_bf16(w[4] * ge[4], w[5] * ge[5]); o.w = cvt_pk_bf16(w[6] * ge[6], w[7] * ge[7]);
;         *(u32x4*)(WT + (size_t)(drow0 + n) * ldt + k0 + 8 * c) = o;
;         if (gam) {
;             float cs = (bf_lo(o.x) + bf_hi(o.x)) + (bf_lo(o.y) + bf_hi(o.y)) + (bf_lo(o.z) + bf_hi(o.z)) + (bf_lo(o.w) + bf_hi(o.w)), bc = 0.f;
; #pragma unroll
;             for (int e = 0; e < 8; ++e) bc += w[e] * be[e];
;             cs += __shfl_xor(cs, 1); cs += __shfl_xor(cs, 2); cs += __shfl_xor(cs, 4); bc += __shfl_xor(bc, 1); bc += __shfl_xor(bc, 2); bc += __shfl_xor(bc, 4);
;             if (c == 0) { csp[(size_t)(k0 >> 6) * N + n0 + n] = cs; bcp[(size_t)(k0 >> 6) * N + n0 + n] = bc; }
;         }
.LBB0_133:
	ds_read2_b32 v[46:47], v13 offset0:8 offset1:41
	ds_read2_b32 v[44:45], v13 offset0:74 offset1:107
	ds_read2_b32 v[42:43], v13 offset0:140 offset1:173
	ds_read2_b32 v[40:41], v13 offset0:206 offset1:239
	v_lshlrev_b32_e32 v72, 11, v57
	s_waitcnt lgkmcnt(3)
	v_mul_f32_e32 v2, v55, v46
	v_mul_f32_e32 v3, v58, v47
	v_cvt_pk_bf16_f32 v2, v2, v3
	s_waitcnt lgkmcnt(2)
	v_mul_f32_e32 v3, v60, v44
	v_mul_f32_e32 v4, v63, v45
	v_cvt_pk_bf16_f32 v3, v3, v4
	s_waitcnt lgkmcnt(1)
	v_mul_f32_e32 v4, v65, v42
	v_mul_f32_e32 v5, v67, v43
	v_mov_b32_e32 v73, v7
	v_cvt_pk_bf16_f32 v4, v4, v5
	s_waitcnt lgkmcnt(0)
	v_mul_f32_e32 v5, v69, v40
	v_lshl_add_u64 v[72:73], v[38:39], 0, v[72:73]
	s_and_b64 vcc, exec, s[4:5]
	v_mul_f32_e32 v62, v71, v41
	v_cvt_pk_bf16_f32 v5, v5, v62
	global_store_dwordx4 v[72:73], v[2:5], off nt
	s_cbranch_vccnz .LBB0_137
	v_lshlrev_b32_e32 v57, 16, v2
	v_and_b32_e32 v2, 0xffff0000, v2
	v_lshlrev_b32_e32 v62, 16, v3
	v_and_b32_e32 v3, 0xffff0000, v3
	v_add_f32_e32 v3, v62, v3
	v_lshlrev_b32_e32 v62, 16, v4
	v_and_b32_e32 v4, 0xffff0000, v4
	v_add_f32_e32 v2, v57, v2
	v_add_f32_e32 v4, v62, v4
	v_add_f32_e32 v2, v2, v3
	v_add_f32_e32 v2, v2, v4
	v_and_b32_e32 v4, 64, v52
	v_xor_b32_e32 v3, 1, v52
	v_add_u32_e32 v4, 64, v4
	v_lshlrev_b32_e32 v62, 16, v5
	v_and_b32_e32 v5, 0xffff0000, v5
	v_cmp_lt_i32_e32 vcc, v3, v4
	v_add_f32_e32 v5, v62, v5
	v_fma_f32 v46, v54, v46, 0
	v_cndmask_b32_e32 v3, v52, v3, vcc
	v_fmac_f32_e32 v46, v56, v47
	v_add_f32_e32 v2, v2, v5
	v_lshlrev_b32_e32 v3, 2, v3
	v_fmac_f32_e32 v46, v59, v44
	ds_bpermute_b32 v5, v3, v2
	v_fmac_f32_e32 v46, v61, v45
	v_fmac_f32_e32 v46, v64, v42
	v_fmac_f32_e32 v46, v66, v43
	v_fmac_f32_e32 v46, v68, v40
	s_waitcnt lgkmcnt(0)
	v_add_f32_e32 v2, v2, v5
	v_xor_b32_e32 v5, 2, v52
	v_fmac_f32_e32 v46, v70, v41
	v_cmp_lt_i32_e32 vcc, v5, v4
	ds_bpermute_b32 v3, v3, v46
	s_waitcnt lgkmcnt(0)
	v_add_f32_e32 v41, v46, v3
	v_cndmask_b32_e32 v5, v52, v5, vcc
	v_lshlrev_b32_e32 v5, 2, v5
	ds_bpermute_b32 v40, v5, v2
	ds_bpermute_b32 v5, v5, v41
	s_waitcnt lgkmcnt(1)
	v_add_f32_e32 v2, v2, v40
	v_xor_b32_e32 v40, 4, v52
	v_cmp_lt_i32_e32 vcc, v40, v4
	s_waitcnt lgkmcnt(0)
	v_add_f32_e32 v4, v41, v5
	v_cndmask_b32_e32 v3, v52, v40, vcc
	v_lshlrev_b32_e32 v40, 2, v3
	ds_bpermute_b32 v3, v40, v2
	ds_bpermute_b32 v5, v40, v4
	s_and_saveexec_b64 s[20:21], s[0:1]
	s_cbranch_execz .LBB0_136
	v_or_b32_e32 v40, s18, v12
	v_lshlrev_b32_e32 v40, 2, v40
	s_waitcnt lgkmcnt(1)
	v_add_f32_e32 v2, v2, v3
	s_waitcnt lgkmcnt(0)
	v_add_f32_e32 v3, v4, v5
	global_store_dword v40, v2, s[8:9]
	global_store_dword v40, v3, s[10:11]

; #define LAS __attribute__((address_space(3)))
; __device__ __forceinline__ unsigned cvt_pk_bf16(float lo, float hi) { unsigned r; asm("v_cvt_pk_bf16_f32 %0, %1, %2" : "=v"(r) : "v"(lo), "v"(hi)); return r; }
; __device__ __forceinline__ float bf_lo(unsigned w) { return __uint_as_float(w << 16); }
; __device__ __forceinline__ float bf_hi(unsigned w) { return __uint_as_float(w & 0xffff0000u); }
; __device__ __forceinline__ void transpose_item(const float* W, int K, int N, bf16_t* WT, int ldt, int k0, int n0, int drow0, LAS float* scr, int lane,
;                                                const float* gam = nullptr, const float* bet = nullptr, float* csp = nullptr, float* bcp = nullptr) {
;     ...
;     for (int j = 0; j < 4; ++j) { const int n = (lane >> 3) + 8 * j; const LAS float* sp = scr + (8 * c) * 33 + n;
;         float w[8];
; #pragma unroll
;         for (int e = 0; e < 8; ++e) w[e] = sp[e * 33];
;         u32x4 o; o.x = cvt_pk_bf16(w[0] * ge[0], w[1] * ge[1]); o.y = cvt_pk_bf16(w[2] * ge[2], w[3] * ge[3]); o.z = cvt_pk_bf16(w[4] * ge[4], w[5] * ge[5]); o.w = cvt_pk_bf16(w[6] * ge[6], w[7] * ge[7]);
;         *(u32x4*)(WT + (size_t)(drow0 + n) * ldt + k0 + 8 * c) = o;
;         if (gam) {
;             float cs = (bf_lo(o.x) + bf_hi(o.x)) + (bf_lo(o.y) + bf_hi(o.y)) + (bf_lo(o.z) + bf_hi(o.z)) + (bf_lo(o.w) + bf_hi(o.w)), bc = 0.f;
; #pragma unroll
;             for (int e = 0; e < 8; ++e) bc += w[e] * be[e];
;             cs += __shfl_xor(cs, 1); cs += __shfl_xor(cs, 2); cs += __shfl_xor(cs, 4); bc += __shfl_xor(bc, 1); bc += __shfl_xor(bc, 2); bc += __shfl_xor(bc, 4);
;             if (c == 0) { csp[(size_t)(k0 >> 6) * N + n0 + n] = cs; bcp[(size_t)(k0 >> 6) * N + n0 + n] = bc; }
;         }
.LBB0_137:
	ds_read2_b32 v[46:47], v13 offset0:16 offset1:49
	ds_read2_b32 v[44:45], v13 offset0:82 offset1:115
	ds_read2_b32 v[42:43], v13 offset0:148 offset1:181
	ds_read2_b32 v[40:41], v13 offset0:214 offset1:247
	v_lshlrev_b32_e32 v72, 11, v53
	s_waitcnt lgkmcnt(3)
	v_mul_f32_e32 v2, v55, v46
	v_mul_f32_e32 v3, v58, v47
	v_cvt_pk_bf16_f32 v2, v2, v3
	s_waitcnt lgkmcnt(2)
	v_mul_f32_e32 v3, v60, v44
	v_mul_f32_e32 v4, v63, v45
	v_cvt_pk_bf16_f32 v3, v3, v4
	s_waitcnt lgkmcnt(1)
	v_mul_f32_e32 v4, v65, v42
	v_mul_f32_e32 v5, v67, v43
	v_mov_b32_e32 v73, v7
	v_cvt_pk_bf16_f32 v4, v4, v5
	s_waitcnt lgkmcnt(0)
	v_mul_f32_e32 v5, v69, v40
	v_lshl_add_u64 v[72:73], v[38:39], 0, v[72:73]
	s_and_b64 vcc, exec, s[4:5]
	v_mul_f32_e32 v57, v71, v41
	v_cvt_pk_bf16_f32 v5, v5, v57
	global_store_dwordx4 v[72:73], v[2:5], off nt
	s_cbranch_vccnz .LBB0_141
	v_lshlrev_b32_e32 v53, 16, v2
	v_and_b32_e32 v2, 0xffff0000, v2
	v_lshlrev_b32_e32 v57, 16, v3
	v_and_b32_e32 v3, 0xffff0000, v3
	v_add_f32_e32 v3, v57, v3
	v_lshlrev_b32_e32 v57, 16, v4
	v_and_b32_e32 v4, 0xffff0000, v4
	v_add_f32_e32 v2, v53, v2
	v_add_f32_e32 v4, v57, v4
	v_add_f32_e32 v2, v2, v3
	v_add_f32_e32 v2, v2, v4
	v_and_b32_e32 v4, 64, v52
	v_xor_b32_e32 v3, 1, v52
	v_add_u32_e32 v4, 64, v4
	v_lshlrev_b32_e32 v57, 16, v5
	v_and_b32_e32 v5, 0xffff0000, v5
	v_cmp_lt_i32_e32 vcc, v3, v4
	v_add_f32_e32 v5, v57, v5
	v_fma_f32 v46, v54, v46, 0
	v_cndmask_b32_e32 v3, v52, v3, vcc
	v_fmac_f32_e32 v46, v56, v47
	v_add_f32_e32 v2, v2, v5
	v_lshlrev_b32_e32 v3, 2, v3
	v_fmac_f32_e32 v46, v59, v44
	ds_bpermute_b32 v5, v3, v2
	v_fmac_f32_e32 v46, v61, v45
	v_fmac_f32_e32 v46, v64, v42
	v_fmac_f32_e32 v46, v66, v43
	v_fmac_f32_e32 v46, v68, v40
	s_waitcnt lgkmcnt(0)
	v_add_f32_e32 v2, v2, v5
	v_xor_b32_e32 v5, 2, v52
	v_fmac_f32_e32 v46, v70, v41
	v_cmp_lt_i32_e32 vcc, v5, v4
	ds_bpermute_b32 v3, v3, v46
	s_waitcnt lgkmcnt(0)
	v_add_f32_e32 v41, v46, v3
	v_cndmask_b32_e32 v5, v52, v5, vcc
	v_lshlrev_b32_e32 v5, 2, v5
	ds_bpermute_b32 v40, v5, v2
	ds_bpermute_b32 v5, v5, v41
	s_waitcnt lgkmcnt(1)
	v_add_f32_e32 v2, v2, v40
	v_xor_b32_e32 v40, 4, v52
	v_cmp_lt_i32_e32 vcc, v40, v4
	s_waitcnt lgkmcnt(0)
	v_add_f32_e32 v4, v41, v5
	v_cndmask_b32_e32 v3, v52, v40, vcc
	v_lshlrev_b32_e32 v40, 2, v3
	ds_bpermute_b32 v3, v40, v2
	ds_bpermute_b32 v5, v40, v4
	s_and_saveexec_b64 s[20:21], s[0:1]
	s_cbranch_execz .LBB0_140
	v_or_b32_e32 v40, s18, v14
	v_lshlrev_b32_e32 v40, 2, v40
	s_waitcnt lgkmcnt(1)
	v_add_f32_e32 v2, v2, v3
	s_waitcnt lgkmcnt(0)
	v_add_f32_e32 v3, v4, v5
	global_store_dword v40, v2, s[8:9]
	global_store_dword v40, v3, s[10:11]

; #define LAS __attribute__((address_space(3)))
; __device__ __forceinline__ unsigned cvt_pk_bf16(float lo, float hi) { unsigned r; asm("v_cvt_pk_bf16_f32 %0, %1, %2" : "=v"(r) : "v"(lo), "v"(hi)); return r; }
; __device__ __forceinline__ float bf_lo(unsigned w) { return __uint_as_float(w << 16); }
; __device__ __forceinline__ float bf_hi(unsigned w) { return __uint_as_float(w & 0xffff0000u); }
; __device__ __forceinline__ void transpose_item(const float* W, int K, int N, bf16_t* WT, int ldt, int k0, int n0, int drow0, LAS float* scr, int lane,
;                                                const float* gam = nullptr, const float* bet = nullptr, float* csp = nullptr, float* bcp = nullptr) {
;     ...
;     for (int j = 0; j < 4; ++j) { const int n = (lane >> 3) + 8 * j; const LAS float* sp = scr + (8 * c) * 33 + n;
;         float w[8];
; #pragma unroll
;         for (int e = 0; e < 8; ++e) w[e] = sp[e * 33];
;         u32x4 o; o.x = cvt_pk_bf16(w[0] * ge[0], w[1] * ge[1]); o.y = cvt_pk_bf16(w[2] * ge[2], w[3] * ge[3]); o.z = cvt_pk_bf16(w[4] * ge[4], w[5] * ge[5]); o.w = cvt_pk_bf16(w[6] * ge[6], w[7] * ge[7]);
;         *(u32x4*)(WT + (size_t)(drow0 + n) * ldt + k0 + 8 * c) = o;
;         if (gam) {
;             float cs = (bf_lo(o.x) + bf_hi(o.x)) + (bf_lo(o.y) + bf_hi(o.y)) + (bf_lo(o.z) + bf_hi(o.z)) + (bf_lo(o.w) + bf_hi(o.w)), bc = 0.f;
; #pragma unroll
;             for (int e = 0; e < 8; ++e) bc += w[e] * be[e];
;             cs += __shfl_xor(cs, 1); cs += __shfl_xor(cs, 2); cs += __shfl_xor(cs, 4); bc += __shfl_xor(bc, 1); bc += __shfl_xor(bc, 2); bc += __shfl_xor(bc, 4);
;             if (c == 0) { csp[(size_t)(k0 >> 6) * N + n0 + n] = cs; bcp[(size_t)(k0 >> 6) * N + n0 + n] = bc; }
;         }
.LBB0_141:
	ds_read2_b32 v[46:47], v13 offset0:24 offset1:57
	ds_read2_b32 v[44:45], v13 offset0:90 offset1:123
	ds_read2_b32 v[42:43], v13 offset0:156 offset1:189
	ds_read2_b32 v[40:41], v13 offset0:222 offset1:255
	v_lshlrev_b32_e32 v62, 11, v37
	s_waitcnt lgkmcnt(3)
	v_mul_f32_e32 v2, v55, v46
	v_mul_f32_e32 v3, v58, v47
	v_cvt_pk_bf16_f32 v2, v2, v3
	s_waitcnt lgkmcnt(2)
	v_mul_f32_e32 v3, v60, v44
	v_mul_f32_e32 v4, v63, v45
	v_cvt_pk_bf16_f32 v3, v3, v4
	s_waitcnt lgkmcnt(1)
	v_mul_f32_e32 v4, v65, v42
	v_mul_f32_e32 v5, v67, v43
	v_mov_b32_e32 v63, v7
	v_cvt_pk_bf16_f32 v4, v4, v5
	s_waitcnt lgkmcnt(0)
	v_mul_f32_e32 v5, v69, v40
	v_lshl_add_u64 v[38:39], v[38:39], 0, v[62:63]
	s_and_b64 vcc, exec, s[4:5]
	v_mul_f32_e32 v53, v71, v41
	v_cvt_pk_bf16_f32 v5, v5, v53
	global_store_dwordx4 v[38:39], v[2:5], off nt
	s_cbranch_vccnz .LBB0_145
	v_lshlrev_b32_e32 v37, 16, v2
	v_and_b32_e32 v2, 0xffff0000, v2
	v_lshlrev_b32_e32 v38, 16, v3
	v_and_b32_e32 v3, 0xffff0000, v3
	v_add_f32_e32 v3, v38, v3
	v_lshlrev_b32_e32 v38, 16, v4
	v_and_b32_e32 v4, 0xffff0000, v4
	v_add_f32_e32 v2, v37, v2
	v_add_f32_e32 v4, v38, v4
	v_add_f32_e32 v2, v2, v3
	v_add_f32_e32 v2, v2, v4
	v_and_b32_e32 v4, 64, v52
	v_xor_b32_e32 v3, 1, v52
	v_add_u32_e32 v4, 64, v4
	v_lshlrev_b32_e32 v38, 16, v5
	v_and_b32_e32 v5, 0xffff0000, v5
	v_cmp_lt_i32_e32 vcc, v3, v4
	v_add_f32_e32 v5, v38, v5
	v_fma_f32 v38, v54, v46, 0
	v_cndmask_b32_e32 v3, v52, v3, vcc
	v_fmac_f32_e32 v38, v56, v47
	v_add_f32_e32 v2, v2, v5
	v_lshlrev_b32_e32 v3, 2, v3
	v_fmac_f32_e32 v38, v59, v44
	ds_bpermute_b32 v5, v3, v2
	v_fmac_f32_e32 v38, v61, v45
	v_fmac_f32_e32 v38, v64, v42
	v_fmac_f32_e32 v38, v66, v43
	v_fmac_f32_e32 v38, v68, v40
	s_waitcnt lgkmcnt(0)
	v_add_f32_e32 v2, v2, v5
	v_xor_b32_e32 v5, 2, v52
	v_fmac_f32_e32 v38, v70, v41
	v_cmp_lt_i32_e32 vcc, v5, v4
	ds_bpermute_b32 v3, v3, v38
	s_waitcnt lgkmcnt(0)
	v_add_f32_e32 v38, v38, v3
	v_cndmask_b32_e32 v5, v52, v5, vcc
	v_lshlrev_b32_e32 v5, 2, v5
	ds_bpermute_b32 v37, v5, v2
	ds_bpermute_b32 v5, v5, v38
	s_waitcnt lgkmcnt(1)
	v_add_f32_e32 v2, v2, v37
	v_xor_b32_e32 v37, 4, v52
	v_cmp_lt_i32_e32 vcc, v37, v4
	s_waitcnt lgkmcnt(0)
	v_add_f32_e32 v4, v38, v5
	v_cndmask_b32_e32 v3, v52, v37, vcc
	v_lshlrev_b32_e32 v37, 2, v3
	ds_bpermute_b32 v3, v37, v2
	ds_bpermute_b32 v5, v37, v4
	s_and_saveexec_b64 s[4:5], s[0:1]
	s_cbranch_execz .LBB0_144
	v_or_b32_e32 v37, s18, v16
	v_lshlrev_b32_e32 v37, 2, v37
	s_waitcnt lgkmcnt(1)
	v_add_f32_e32 v2, v2, v3
	s_waitcnt lgkmcnt(0)
	v_add_f32_e32 v3, v4, v5
	global_store_dword v37, v2, s[8:9]
	global_store_dword v37, v3, s[10:11]

; __device__ __forceinline__ void transpose_item(const float* W, int K, int N, bf16_t* WT, int ldt, int k0, int n0, int drow0, LAS float* scr, int lane,
;                                                const float* gam = nullptr, const float* bet = nullptr, float* csp = nullptr, float* bcp = nullptr) {
;     float tv[32];
; #pragma unroll
;     for (int i = 0; i < 32; ++i) tv[i] = __builtin_nontemporal_load(W + (size_t)(k0 + 2 * i + (lane >> 5)) * N + n0 + (lane & 31));
; #pragma unroll
;     for (int i = 0; i < 32; ++i) scr[(2 * i + (lane >> 5)) * 33 + (lane & 31)] = tv[i];
.LBB0_147:
	s_andn2_b64 vcc, exec, s[4:5]
	s_cbranch_vccnz .LBB0_149
	s_and_b32 s4, s35, 0xfc0
	s_addk_i32 s4, 0xf400
	s_and_b32 s20, s27, 0x1e0
	v_or_b32_e32 v2, s4, v9
	s_lshl_b32 s18, s20, 2
	s_waitcnt lgkmcnt(1)
	v_mov_b32_e32 v3, v7
	v_or_b32_e32 v40, 2, v2
	v_mov_b32_e32 v41, v7
	v_or_b32_e32 v42, 4, v2
	v_mov_b32_e32 v43, v7
	v_or_b32_e32 v44, 6, v2
	v_mov_b32_e32 v45, v7
	v_or_b32_e32 v46, 8, v2
	v_mov_b32_e32 v47, v7
	v_or_b32_e32 v54, 10, v2
	v_mov_b32_e32 v55, v7
	v_or_b32_e32 v56, 12, v2
	v_mov_b32_e32 v57, v7
	v_or_b32_e32 v58, 14, v2
	v_mov_b32_e32 v59, v7
	s_waitcnt lgkmcnt(0)
	v_lshl_add_u64 v[4:5], v[30:31], 0, s[18:19]
	v_lshlrev_b64 v[38:39], 11, v[2:3]
	v_lshlrev_b64 v[40:41], 11, v[40:41]
	v_lshlrev_b64 v[42:43], 11, v[42:43]
	v_lshlrev_b64 v[44:45], 11, v[44:45]
	v_lshlrev_b64 v[46:47], 11, v[46:47]
	v_lshlrev_b64 v[54:55], 11, v[54:55]
	v_lshlrev_b64 v[56:57], 11, v[56:57]
	v_lshlrev_b64 v[58:59], 11, v[58:59]
	v_lshl_add_u64 v[38:39], v[4:5], 0, v[38:39]
	v_lshl_add_u64 v[40:41], v[4:5], 0, v[40:41]
	v_lshl_add_u64 v[42:43], v[4:5], 0, v[42:43]
	v_lshl_add_u64 v[44:45], v[4:5], 0, v[44:45]
	v_lshl_add_u64 v[46:47], v[4:5], 0, v[46:47]
	v_lshl_add_u64 v[54:55], v[4:5], 0, v[54:55]
	v_lshl_add_u64 v[56:57], v[4:5], 0, v[56:57]
	v_lshl_add_u64 v[58:59], v[4:5], 0, v[58:59]
	global_load_dword v37, v[38:39], off nt
	global_load_dword v53, v[40:41], off nt
	global_load_dword v60, v[42:43], off nt
	global_load_dword v61, v[44:45], off nt
	global_load_dword v62, v[46:47], off nt
	global_load_dword v63, v[54:55], off nt
	global_load_dword v64, v[56:57], off nt
	global_load_dword v65, v[58:59], off nt
	v_or_b32_e32 v38, 16, v2
	v_mov_b32_e32 v39, v7
	v_or_b32_e32 v40, 18, v2
	v_mov_b32_e32 v41, v7
	v_or_b32_e32 v42, 20, v2
	v_mov_b32_e32 v43, v7
	v_or_b32_e32 v44, 22, v2
	v_mov_b32_e32 v45, v7
	v_or_b32_e32 v46, 24, v2
	v_mov_b32_e32 v47, v7
	v_or_b32_e32 v54, 26, v2
	v_mov_b32_e32 v55, v7
	v_or_b32_e32 v56, 28, v2
	v_mov_b32_e32 v57, v7
	v_or_b32_e32 v58, 30, v2
	v_mov_b32_e32 v59, v7
	v_lshlrev_b64 v[38:39], 11, v[38:39]
	v_lshlrev_b64 v[40:41], 11, v[40:41]
	v_lshlrev_b64 v[42:43], 11, v[42:43]
	v_lshlrev_b64 v[44:45], 11, v[44:45]
	v_lshlrev_b64 v[46:47], 11, v[46:47]
	v_lshlrev_b64 v[54:55], 11, v[54:55]
	v_lshlrev_b64 v[56:57], 11, v[56:57]
	v_lshlrev_b64 v[58:59], 11, v[58:59]
	v_lshl_add_u64 v[38:39], v[4:5], 0, v[38:39]
	v_lshl_add_u64 v[40:41], v[4:5], 0, v[40:41]
	v_lshl_add_u64 v[42:43], v[4:5], 0, v[42:43]
	v_lshl_add_u64 v[44:45], v[4:5], 0, v[44:45]
	v_lshl_add_u64 v[46:47], v[4:5], 0, v[46:47]
	v_lshl_add_u64 v[54:55], v[4:5], 0, v[54:55]
	v_lshl_add_u64 v[56:57], v[4:5], 0, v[56:57]
	v_lshl_add_u64 v[58:59], v[4:5], 0, v[58:59]
	global_load_dword v66, v[38:39], off nt
	global_load_dword v67, v[40:41], off nt
	global_load_dword v68, v[42:43], off nt
	global_load_dword v69, v[44:45], off nt
	global_load_dword v70, v[46:47], off nt
	global_load_dword v71, v[54:55], off nt
	global_load_dword v72, v[56:57], off nt
	global_load_dword v73, v[58:59], off nt
	v_or_b32_e32 v38, 32, v2
	v_mov_b32_e32 v39, v7
	v_or_b32_e32 v40, 34, v2
	v_mov_b32_e32 v41, v7
	v_or_b32_e32 v42, 36, v2
	v_mov_b32_e32 v43, v7
	v_or_b32_e32 v44, 38, v2
	v_mov_b32_e32 v45, v7
	v_or_b32_e32 v46, 40, v2
	v_mov_b32_e32 v47, v7
	v_or_b32_e32 v54, 42, v2
	v_mov_b32_e32 v55, v7
	v_or_b32_e32 v56, 44, v2
	v_mov_b32_e32 v57, v7
	v_or_b32_e32 v58, 46, v2
	v_mov_b32_e32 v59, v7
	v_lshlrev_b64 v[38:39], 11, v[38:39]
	v_lshlrev_b64 v[40:41], 11, v[40:41]
	v_lshlrev_b64 v[42:43], 11, v[42:43]
	v_lshlrev_b64 v[44:45], 11, v[44:45]
	v_lshlrev_b64 v[46:47], 11, v[46:47]
	v_lshlrev_b64 v[54:55], 11, v[54:55]
	v_lshlrev_b64 v[56:57], 11, v[56:57]
	v_lshlrev_b64 v[58:59], 11, v[58:59]
	v_lshl_add_u64 v[38:39], v[4:5], 0, v[38:39]
	v_lshl_add_u64 v[40:41], v[4:5], 0, v[40:41]
	v_lshl_add_u64 v[42:43], v[4:5], 0, v[42:43]
	v_lshl_add_u64 v[44:45], v[4:5], 0, v[44:45]
	v_lshl_add_u64 v[46:47], v[4:5], 0, v[46:47]
	v_lshl_add_u64 v[54:55], v[4:5], 0, v[54:55]
	v_lshl_add_u64 v[56:57], v[4:5], 0, v[56:57]
	v_lshl_add_u64 v[58:59], v[4:5], 0, v[58:59]
	global_load_dword v74, v[38:39], off nt
	global_load_dword v75, v[40:41], off nt
	global_load_dword v76, v[42:43], off nt
	global_load_dword v77, v[44:45], off nt
	global_load_dword v78, v[46:47], off nt
	global_load_dword v79, v[54:55], off nt
	global_load_dword v80, v[56:57], off nt
	s_nop 0
	global_load_dword v58, v[58:59], off nt
	v_or_b32_e32 v38, 48, v2
	v_mov_b32_e32 v39, v7
	v_or_b32_e32 v40, 50, v2
	v_mov_b32_e32 v41, v7
	v_or_b32_e32 v42, 52, v2
	v_mov_b32_e32 v43, v7
	v_or_b32_e32 v44, 54, v2
	v_or_b32_e32 v46, 56, v2
	v_or_b32_e32 v54, 58, v2
	v_or_b32_e32 v56, 60, v2
	v_or_b32_e32 v2, 62, v2
	v_lshlrev_b64 v[38:39], 11, v[38:39]
	v_lshlrev_b64 v[40:41], 11, v[40:41]
	v_lshlrev_b64 v[42:43], 11, v[42:43]
	v_mov_b32_e32 v45, v7
	v_mov_b32_e32 v47, v7
	v_mov_b32_e32 v55, v7
	v_mov_b32_e32 v57, v7
	v_lshlrev_b64 v[2:3], 11, v[2:3]
	v_lshl_add_u64 v[38:39], v[4:5], 0, v[38:39]
	v_lshl_add_u64 v[40:41], v[4:5], 0, v[40:41]
	v_lshl_add_u64 v[42:43], v[4:5], 0, v[42:43]
	v_lshlrev_b64 v[44:45], 11, v[44:45]
	v_lshlrev_b64 v[46:47], 11, v[46:47]
	v_lshlrev_b64 v[54:55], 11, v[54:55]
	v_lshlrev_b64 v[56:57], 11, v[56:57]
	v_lshl_add_u64 v[2:3], v[4:5], 0, v[2:3]
	v_lshl_add_u64 v[44:45], v[4:5], 0, v[44:45]
	v_lshl_add_u64 v[46:47], v[4:5], 0, v[46:47]
	v_lshl_add_u64 v[54:55], v[4:5], 0, v[54:55]
	v_lshl_add_u64 v[56:57], v[4:5], 0, v[56:57]
	global_load_dword v4, v[38:39], off nt
	global_load_dword v5, v[40:41], off nt
	s_nop 0
	global_load_dword v38, v[42:43], off nt
	global_load_dword v39, v[44:45], off nt
	global_load_dword v40, v[46:47], off nt
	global_load_dword v41, v[54:55], off nt
	s_nop 0
	global_load_dword v42, v[56:57], off nt
	s_nop 0
	global_load_dword v2, v[2:3], off nt
	s_waitcnt vmcnt(30)
; #define LAS __attribute__((address_space(3)))
; __device__ __forceinline__ unsigned cvt_pk_bf16(float lo, float hi) { unsigned r; asm("v_cvt_pk_bf16_f32 %0, %1, %2" : "=v"(r) : "v"(lo), "v"(hi)); return r; }
; __device__ __forceinline__ void transpose_item(const float* W, int K, int N, bf16_t* WT, int ldt, int k0, int n0, int drow0, LAS float* scr, int lane,
;                                                const float* gam = nullptr, const float* bet = nullptr, float* csp = nullptr, float* bcp = nullptr) {
;     ...
;     for (int i = 0; i < 32; ++i) scr[(2 * i + (lane >> 5)) * 33 + (lane & 31)] = tv[i];
;     asm volatile("s_waitcnt lgkmcnt(0)" ::: "memory");
;     const int c = lane & 7;
;     float ge[8], be[8];
; #pragma unroll
;     for (int e = 0; e < 8; ++e) { ge[e] = gam ? gam[k0 + 8 * c + e] : 1.f; be[e] = gam ? bet[k0 + 8 * c + e] : 0.f; }
; #pragma unroll
;     for (int j = 0; j < 4; ++j) { const int n = (lane >> 3) + 8 * j; const LAS float* sp = scr + (8 * c) * 33 + n;
;         float w[8];
; #pragma unroll
;         for (int e = 0; e < 8; ++e) w[e] = sp[e * 33];
;         u32x4 o; o.x = cvt_pk_bf16(w[0] * ge[0], w[1] * ge[1]); o.y = cvt_pk_bf16(w[2] * ge[2], w[3] * ge[3]); o.z = cvt_pk_bf16(w[4] * ge[4], w[5] * ge[5]); o.w = cvt_pk_bf16(w[6] * ge[6], w[7] * ge[7]);
;         *(u32x4*)(WT + (size_t)(drow0 + n) * ldt + k0 + 8 * c) = o;
	ds_write2_b32 v11, v37, v53 offset1:66
	s_waitcnt vmcnt(28)
	ds_write2_b32 v11, v60, v61 offset0:132 offset1:198
	s_waitcnt vmcnt(26)
	ds_write2_b32 v15, v62, v63 offset0:8 offset1:74
	s_waitcnt vmcnt(24)
	ds_write2_b32 v15, v64, v65 offset0:140 offset1:206
	s_waitcnt vmcnt(22)
	ds_write2_b32 v17, v66, v67 offset0:16 offset1:82
	s_waitcnt vmcnt(20)
	ds_write2_b32 v17, v68, v69 offset0:148 offset1:214
	s_waitcnt vmcnt(18)
	ds_write2_b32 v35, v70, v71 offset0:24 offset1:90
	s_waitcnt vmcnt(16)
	ds_write2_b32 v35, v72, v73 offset0:156 offset1:222
	s_waitcnt vmcnt(14)
	ds_write2_b32 v48, v74, v75 offset0:32 offset1:98
	s_waitcnt vmcnt(12)
	ds_write2_b32 v48, v76, v77 offset0:164 offset1:230
	s_waitcnt vmcnt(10)
	ds_write2_b32 v49, v78, v79 offset0:40 offset1:106
	s_waitcnt vmcnt(8)
	ds_write2_b32 v49, v80, v58 offset0:172 offset1:238
	s_waitcnt vmcnt(6)
	ds_write2_b32 v50, v4, v5 offset0:48 offset1:114
	s_waitcnt vmcnt(4)
	ds_write2_b32 v50, v38, v39 offset0:180 offset1:246
	s_waitcnt vmcnt(2)
	ds_write2_b32 v51, v40, v41 offset0:56 offset1:122
	s_waitcnt vmcnt(0)
	ds_write2_b32 v51, v42, v2 offset0:188 offset1:254
	s_waitcnt lgkmcnt(0)
	ds_read2_b32 v[38:39], v13 offset1:8
	ds_read2_b32 v[40:41], v13 offset0:33 offset1:41
	ds_read2_b32 v[42:43], v13 offset0:66 offset1:74
	ds_read2_b32 v[44:45], v13 offset0:99 offset1:107
	ds_read2_b32 v[46:47], v13 offset0:132 offset1:140
	ds_read2_b32 v[54:55], v13 offset0:165 offset1:173
	ds_read2_b32 v[56:57], v13 offset0:198 offset1:206
	ds_read2_b32 v[58:59], v13 offset0:231 offset1:239
	s_mov_b32 s5, s19
	v_or_b32_e32 v37, s20, v10
	v_lshl_add_u64 v[60:61], s[4:5], 1, v[22:23]
	v_lshlrev_b32_e32 v62, 10, v37
	v_mov_b32_e32 v63, v7
	v_lshl_add_u64 v[62:63], v[60:61], 0, v[62:63]
	s_waitcnt lgkmcnt(6)
	v_cvt_pk_bf16_f32 v2, v38, v40
	s_waitcnt lgkmcnt(4)
	v_cvt_pk_bf16_f32 v3, v42, v44
	s_waitcnt lgkmcnt(2)
	v_cvt_pk_bf16_f32 v4, v46, v54
	s_waitcnt lgkmcnt(0)
	v_cvt_pk_bf16_f32 v5, v56, v58
	global_store_dwordx4 v[62:63], v[2:5], off nt
	v_or_b32_e32 v37, s20, v12
	v_lshlrev_b32_e32 v38, 10, v37
	v_cvt_pk_bf16_f32 v2, v39, v41
	v_cvt_pk_bf16_f32 v3, v43, v45
	v_cvt_pk_bf16_f32 v4, v47, v55
	v_cvt_pk_bf16_f32 v5, v57, v59
	ds_read2_b32 v[40:41], v13 offset0:16 offset1:24
	ds_read2_b32 v[42:43], v13 offset0:49 offset1:57
	ds_read2_b32 v[44:45], v13 offset0:82 offset1:90
	ds_read2_b32 v[46:47], v13 offset0:115 offset1:123
	ds_read2_b32 v[54:55], v13 offset0:148 offset1:156
	ds_read2_b32 v[56:57], v13 offset0:181 offset1:189
	ds_read2_b32 v[58:59], v13 offset0:214 offset1:222
	ds_read2_b32 v[62:63], v13 offset0:247 offset1:255
	v_mov_b32_e32 v39, v7
	v_lshl_add_u64 v[38:39], v[60:61], 0, v[38:39]
	v_or_b32_e32 v37, s20, v14
	global_store_dwordx4 v[38:39], v[2:5], off nt
	v_lshlrev_b32_e32 v38, 10, v37
	v_mov_b32_e32 v39, v7
	v_lshl_add_u64 v[38:39], v[60:61], 0, v[38:39]
	v_or_b32_e32 v37, s20, v16
	s_waitcnt lgkmcnt(6)
	v_cvt_pk_bf16_f32 v2, v40, v42
	s_waitcnt lgkmcnt(4)
	v_cvt_pk_bf16_f32 v3, v44, v46
	s_waitcnt lgkmcnt(2)
	v_cvt_pk_bf16_f32 v4, v54, v56
	s_waitcnt lgkmcnt(0)
	v_cvt_pk_bf16_f32 v5, v58, v62
	global_store_dwordx4 v[38:39], v[2:5], off nt
	v_lshlrev_b32_e32 v38, 10, v37
	v_mov_b32_e32 v39, v7
	v_lshl_add_u64 v[38:39], v[60:61], 0, v[38:39]
	v_cvt_pk_bf16_f32 v2, v41, v43
	v_cvt_pk_bf16_f32 v3, v45, v47
	v_cvt_pk_bf16_f32 v4, v55, v57
	v_cvt_pk_bf16_f32 v5, v59, v63
	global_store_dwordx4 v[38:39], v[2:5], off nt
	s_waitcnt lgkmcnt(0)
